# MLA attention loop: loop-invariant V-read LDS address term hoisted to the item preheader (on top of the MoBA hoist)
# speedup vs baseline: 1.0017x; 1.0017x over previous
; __device__ __forceinline__ bf16_t cvt_bf16(float v) { return (bf16_t)(cvt_pk_bf16(v, 0.f) & 0xffffu); }
; template <int DQ, int TYPE>
; __device__ __forceinline__ void attn_item(PP p, int layer, int b, int h, int qt, char* lds, const int tid_, unsigned* next_ctr, volatile XLAS unsigned* slot) {
;     ...
;             for (int kk = 0; kk < 2; ++kk) {
;                 bf16x8 x1 = qf[8 + kk], x2 = qf[10 + kk], o1, o2;
; #pragma unroll
;                 for (int j = 0; j < 8; ++j) {
;                     const int f = 16 * kk + 8 * hh + j;
;                     const float cs = r64[2 * f], sn = r64[2 * f + 1];
;                     const float a = __uint_as_float(((unsigned)(unsigned short)x1[j]) << 16), bb = __uint_as_float(((unsigned)(unsigned short)x2[j]) << 16);
;                     o1[j] = (short)cvt_bf16(a * cs - bb * sn); o2[j] = (short)cvt_bf16(bb * cs + a * sn);
;                 }
;                 qf[8 + kk] = o1; qf[10 + kk] = o2;
;             }
;     ...
;     f32x16 O[4];
; #pragma unroll
;     for (int md = 0; md < 4; ++md)
; #pragma unroll
;         for (int i = 0; i < 16; ++i) O[md][i] = 0.f;
;     float m_run = -1e30f, l_run = 0.f;
;     if (TYPE == 2 && kh == 0) { m_run = p->sinks[layer * 8 + h] * LOG2E; l_run = (hh == 0) ? 1.f : 0.f; }
;     constexpr int GK = (DQ == 192) ? 3 : 4, NG = NKS / GK;
;     A_LSTORE(A, 0); __syncthreads();
;     if (kh == 0) __builtin_amdgcn_s_setprio(2);
; #pragma unroll 1
;     for (int j = j_lo; j <= j_hi; ++j) {
.LBB0_661:
	s_ashr_i32 s56, s14, 8
	v_lshl_add_u64 v[190:191], s[12:13], 0, v[0:1]
	s_lshl_b32 s17, s56, 5
	s_mov_b32 s12, 0x5040100
	v_or_b32_e32 v18, s17, v154
	v_perm_b32 v140, v35, v34, s12
	v_mov_b32_e32 v34, v1
	v_mov_b32_e32 v35, v1
	v_mov_b32_e32 v48, v1
	v_mov_b32_e32 v49, v1
	v_mul_lo_u32 v196, v18, s51
	v_perm_b32 v137, v30, v28, s12
	v_perm_b32 v136, v27, v26, s12
	v_perm_b32 v135, v25, v24, s12
	v_perm_b32 v134, v23, v22, s12
	v_perm_b32 v141, v9, v36, s12
	v_perm_b32 v139, v33, v32, s12
	v_perm_b32 v138, v31, v29, s12
	v_perm_b32 v145, v17, v16, s12
	v_perm_b32 v144, v12, v15, s12
	v_perm_b32 v143, v11, v14, s12
	v_perm_b32 v142, v10, v19, s12
	v_perm_b32 v149, v5, v8, s12
	v_perm_b32 v148, v4, v7, s12
	v_perm_b32 v147, v3, v6, s12
	v_perm_b32 v146, v2, v13, s12
	s_lshl_b32 s12, s49, 1
	v_mov_b32_e32 v36, v1
	v_mov_b32_e32 v37, v1
	v_mov_b32_e32 v38, v1
	v_mov_b32_e32 v39, v1
	v_mov_b32_e32 v40, v1
	v_mov_b32_e32 v41, v1
	v_mov_b32_e32 v42, v1
	v_mov_b32_e32 v43, v1
	v_mov_b32_e32 v44, v1
	v_mov_b32_e32 v45, v1
	v_mov_b32_e32 v46, v1
	v_mov_b32_e32 v47, v1
	v_mov_b64_e32 v[64:65], v[48:49]
	v_mov_b64_e32 v[2:3], v[34:35]
	v_mov_b64_e32 v[18:19], v[34:35]
	v_mul_u32_u24_e32 v195, 17, v185
	s_lshl_b32 s16, s80, 1
	s_or_b32 s50, s15, 31
	v_and_b32_e32 v244, 7, v154
	v_lshrrev_b32_e32 v245, 3, v154
	v_mad_u32_u24 v244, v244, 18, v245
	v_mul_u32_u24_e32 v197, 0x88, v244
	v_lshlrev_b32_e32 v187, 2, v155
	s_sub_i32 s49, 64, s12
	s_mov_b32 s51, 0
	v_mov_b32_e32 v199, 0
	v_mov_b32_e32 v205, 0xf149f2ca
	v_lshlrev_b32_e32 v198, 1, v153
	s_mov_b32 s57, s17
	v_mov_b64_e32 v[62:63], v[46:47]
	v_mov_b64_e32 v[60:61], v[44:45]
	v_mov_b64_e32 v[58:59], v[42:43]
	v_mov_b64_e32 v[56:57], v[40:41]
	v_mov_b64_e32 v[54:55], v[38:39]
	v_mov_b64_e32 v[52:53], v[36:37]
	v_mov_b64_e32 v[50:51], v[34:35]
	v_mov_b64_e32 v[4:5], v[36:37]
	v_mov_b64_e32 v[6:7], v[38:39]
	v_mov_b64_e32 v[8:9], v[40:41]
	v_mov_b64_e32 v[10:11], v[42:43]
	v_mov_b64_e32 v[12:13], v[44:45]
	v_mov_b64_e32 v[14:15], v[46:47]
	v_mov_b64_e32 v[16:17], v[48:49]
	v_mov_b64_e32 v[20:21], v[36:37]
	v_mov_b64_e32 v[22:23], v[38:39]
	v_mov_b64_e32 v[24:25], v[40:41]
	v_mov_b64_e32 v[26:27], v[42:43]
	v_mov_b64_e32 v[28:29], v[44:45]
	v_mov_b64_e32 v[30:31], v[46:47]
	v_mov_b64_e32 v[32:33], v[48:49]
	v_lshl_add_u32 v244, v187, 1, v197
	s_mov_b32 s98, 0x20000
	s_mov_b32 s99, 0
	v_lshlrev_b64 v[232:233], 11, v[166:167]
	v_lshlrev_b64 v[234:235], 11, v[168:169]
	v_lshlrev_b64 v[236:237], 11, v[170:171]
	v_lshlrev_b64 v[238:239], 7, v[174:175]
	v_lshl_add_u64 v[232:233], v[176:177], 0, v[232:233]
	v_lshl_add_u64 v[234:235], v[176:177], 0, v[234:235]
	v_lshl_add_u64 v[236:237], v[176:177], 0, v[236:237]
	v_lshl_add_u64 v[238:239], v[190:191], 0, v[238:239]
	v_lshl_add_u64 v[232:233], s[98:99], 0, v[232:233]
	v_lshl_add_u64 v[234:235], s[98:99], 0, v[234:235]
	v_lshl_add_u64 v[236:237], s[98:99], 0, v[236:237]
	v_add_co_u32_e32 v238, vcc, 0x2000, v238
	v_addc_co_u32_e32 v239, vcc, 0, v239, vcc
	s_cmp_le_u32 s51, s16
	s_cselect_b64 s[12:13], -1, 0
	s_cmp_gt_u32 s51, s16
	s_cbranch_scc1 .LBB0_664
	s_branch .LBB0_663

; template <int DQ, int TYPE>
; __device__ __forceinline__ void attn_item(PP p, int layer, int b, int h, int qt, char* lds, const int tid_, unsigned* next_ctr, volatile XLAS unsigned* slot) {
;     ...
;             const bf16_t* Ks = (const bf16_t*)(lds + buf * STAGE); const bf16_t* Vt = (const bf16_t*)(lds + buf * STAGE + KBYTES);
;             f32x16 sacc;
; #pragma unroll
;             for (int i = 0; i < 16; ++i) sacc[i] = 0.f;
;             const bf16_t* kb_ = Ks + (32 * kh + r) * KLD + 8 * hh;
;             bf16x8 kf[2][GK];
; #pragma unroll
;             for (int i = 0; i < GK; ++i) kf[0][i] = *(const bf16x8*)(kb_ + 16 * i);
; #pragma unroll
;             for (int g = 0; g < NG; ++g) {
;                 if (g + 1 < NG) {
; #pragma unroll
;                     for (int i = 0; i < GK; ++i) kf[(g + 1) & 1][i] = *(const bf16x8*)(kb_ + 16 * ((g + 1) * GK + i));
;                 }
;                 __builtin_amdgcn_sched_barrier(0);
; #pragma unroll
;                 for (int i = 0; i < GK; ++i) sacc = __builtin_amdgcn_mfma_f32_32x32x16_bf16(kf[g & 1][i], qf[g * GK + i], sacc, 0, 0, 0);
;                 __builtin_amdgcn_sched_barrier(0);
;             }
;             const bf16_t* vb0 = Vt + r * VLD + 32 * kh + 4 * hh;
;             u32x2 vf[2][4][2];
; #pragma unroll
;             for (int md = 0; md < 4; ++md) { vf[0][md][0] = *(const u32x2*)(vb0 + md * 32 * VLD); vf[0][md][1] = *(const u32x2*)(vb0 + md * 32 * VLD + 8); }
;             if (mode != 0) {
;                 const bool selbit = (qmask >> (j >> 2)) & 1u;
; #pragma unroll
;                 for (int i = 0; i < 16; ++i) {
;                     const int kpos = kbase_pos + 8 * (i >> 2) + 4 * hh + (i & 3);
;                     const int dd = qpos - kpos;
;                     bool ok;
;                     if (mode == 1) ok = dd >= 0; else if (mode == 2) ok = (dd >= 0 && dd < 128); else ok = selbit;
;                     if (!ok) sacc[i] = -INFINITY;
;                 }
;             }
.LBB0_664:
	s_and_b32 s58, s51, 1
	s_cmp_ge_u32 s51, s16
	s_cselect_b64 s[14:15], -1, 0
	s_cmp_gt_i32 s57, s50
	s_cselect_b64 s[60:61], -1, 0
	s_and_b64 s[60:61], s[14:15], s[60:61]
	s_and_b64 vcc, exec, s[60:61]
	s_cbranch_vccnz .LBB0_670
	s_mul_i32 s59, s58, 0xaf70
	s_add_i32 s59, s59, 16
	v_add3_u32 v192, s59, v196, v198
	ds_read_b128 v[66:69], v192
	ds_read_b128 v[150:153], v192 offset:32
	ds_read_b128 v[154:157], v192 offset:64
	ds_read_b128 v[158:161], v192 offset:96
	ds_read_b128 v[162:165], v192 offset:128
	ds_read_b128 v[200:203], v192 offset:160
	s_waitcnt lgkmcnt(5)
	v_mfma_f32_32x32x16_bf16 v[66:81], v[66:69], v[94:97], 0
	s_waitcnt lgkmcnt(4)
	v_mfma_f32_32x32x16_bf16 v[66:81], v[150:153], v[98:101], v[66:81]
	s_waitcnt lgkmcnt(3)
	v_mfma_f32_32x32x16_bf16 v[66:81], v[154:157], v[102:105], v[66:81]
	ds_read_b128 v[150:153], v192 offset:192
	ds_read_b128 v[154:157], v192 offset:224
	ds_read_b128 v[206:209], v192 offset:256
	s_waitcnt lgkmcnt(5)
	v_mfma_f32_32x32x16_bf16 v[66:81], v[158:161], v[106:109], v[66:81]
	s_waitcnt lgkmcnt(4)
	v_mfma_f32_32x32x16_bf16 v[66:81], v[162:165], v[110:113], v[66:81]
	s_waitcnt lgkmcnt(3)
	v_mfma_f32_32x32x16_bf16 v[66:81], v[200:203], v[126:129], v[66:81]
	ds_read_b128 v[158:161], v192 offset:288
	ds_read_b128 v[210:213], v192 offset:320
	ds_read_b128 v[240:243], v192 offset:352
	s_waitcnt lgkmcnt(5)
	v_mfma_f32_32x32x16_bf16 v[66:81], v[150:153], v[130:133], v[66:81]
	s_waitcnt lgkmcnt(4)
	v_mfma_f32_32x32x16_bf16 v[66:81], v[154:157], v[82:85], v[66:81]
	s_waitcnt lgkmcnt(3)
	v_mfma_f32_32x32x16_bf16 v[66:81], v[206:209], v[134:137], v[66:81]
	s_waitcnt lgkmcnt(2)
	v_mfma_f32_32x32x16_bf16 v[66:81], v[158:161], v[138:141], v[66:81]
	s_lshl_b32 s60, s17, 1
	s_add_i32 s60, s60, s59
	v_add_u32_e32 v150, s60, v244
	v_add_u32_e32 v203, 0x6000, v150
	v_add_u32_e32 v201, 0x6120, v150
	v_add_u32_e32 v204, 0x6240, v150
	s_waitcnt lgkmcnt(1)
	v_mfma_f32_32x32x16_bf16 v[66:81], v[210:213], v[142:145], v[66:81]
	v_add_u32_e32 v202, 0x6360, v150
	ds_read2_b64 v[162:165], v203 offset0:128 offset1:130
	ds_read2_b64 v[158:161], v201 offset0:160 offset1:162
	ds_read2_b64 v[154:157], v204 offset0:192 offset1:194
	ds_read2_b64 v[150:153], v202 offset0:224 offset1:226
	s_andn2_b64 vcc, exec, s[14:15]
	s_waitcnt lgkmcnt(4)
	v_mfma_f32_32x32x16_bf16 v[66:81], v[240:243], v[146:149], v[66:81]
	s_cbranch_vccnz .LBB0_667
	v_add_u32_e32 v192, s57, v187
	v_cmp_gt_i32_e32 vcc, v172, v192
	v_add_u32_e32 v200, 2, v192
	s_nop 7
	v_cndmask_b32_e32 v67, v225, v67, vcc
	v_cmp_ge_i32_e32 vcc, v172, v192
	s_nop 1
	v_cndmask_b32_e32 v66, v225, v66, vcc
	v_cmp_ge_i32_e32 vcc, v172, v200
	v_add_u32_e32 v200, 3, v192
	s_nop 0
	v_cndmask_b32_e32 v68, v225, v68, vcc
	v_cmp_ge_i32_e32 vcc, v172, v200
	v_add_u32_e32 v200, 8, v192
	s_nop 0
	v_cndmask_b32_e32 v69, v225, v69, vcc
	v_cmp_ge_i32_e32 vcc, v172, v200
	v_add_u32_e32 v200, 9, v192
	s_nop 0
	v_cndmask_b32_e32 v70, v225, v70, vcc
	v_cmp_ge_i32_e32 vcc, v172, v200
	v_add_u32_e32 v200, 10, v192
	s_nop 0
	v_cndmask_b32_e32 v71, v225, v71, vcc
	v_cmp_ge_i32_e32 vcc, v172, v200
	v_add_u32_e32 v200, 11, v192
	s_nop 0
	v_cndmask_b32_e32 v72, v225, v72, vcc
	v_cmp_ge_i32_e32 vcc, v172, v200
	v_add_u32_e32 v200, 16, v192
	s_nop 0
	v_cndmask_b32_e32 v73, v225, v73, vcc
	v_cmp_ge_i32_e32 vcc, v172, v200
	v_add_u32_e32 v200, 17, v192
	s_nop 0
	v_cndmask_b32_e32 v74, v225, v74, vcc
	v_cmp_ge_i32_e32 vcc, v172, v200
	v_add_u32_e32 v200, 18, v192
	s_nop 0
	v_cndmask_b32_e32 v75, v225, v75, vcc
	v_cmp_ge_i32_e32 vcc, v172, v200
	v_add_u32_e32 v200, 19, v192
	s_nop 0
	v_cndmask_b32_e32 v76, v225, v76, vcc
	v_cmp_ge_i32_e32 vcc, v172, v200
	v_add_u32_e32 v200, 24, v192
	s_nop 0
	v_cndmask_b32_e32 v77, v225, v77, vcc
	v_cmp_ge_i32_e32 vcc, v172, v200
	v_add_u32_e32 v200, 25, v192
	s_nop 0
	v_cndmask_b32_e32 v78, v225, v78, vcc
	v_cmp_ge_i32_e32 vcc, v172, v200
	v_add_u32_e32 v200, 26, v192
	v_add_u32_e32 v192, 27, v192
	v_cndmask_b32_e32 v79, v225, v79, vcc
	v_cmp_ge_i32_e32 vcc, v172, v200
	s_nop 1
	v_cndmask_b32_e32 v80, v225, v80, vcc
	v_cmp_ge_i32_e32 vcc, v172, v192
	s_nop 1
	v_cndmask_b32_e32 v81, v225, v81, vcc
